# hgrn pass C: IEEE f32 division expansions replaced by v_rcp+v_mul (33 per chunk); hgrn ushort loads in saddr form (no 64-bit VALU address adds)
# speedup vs baseline: 1.0169x; 1.0095x over previous
.LBB0_443:
	s_and_b32 s0, s50, 0xffffe000
	s_and_b32 s1, s52, 0x1e00
	s_or_b32 s4, s0, s1
	s_lshl_b32 s1, s22, 6
	s_lshl_b32 s5, s22, 9
	s_ashr_i32 s54, s22, 4
	s_and_b32 s1, s1, 0xffffe000
	s_and_b32 s5, s5, 0x1e00
	s_lshl_b32 s0, s54, 7
	s_or_b32 s1, s1, s5
	s_bitset1_b32 s4, 7
	s_and_b32 s0, s0, 0x380
	s_mul_hi_i32 s5, s1, 0x3800
	s_mulk_i32 s1, 0x3800
	s_add_u32 s1, s37, s1
	s_addc_u32 s6, s46, s5
	s_lshl_b32 s5, s0, 1
	v_or_b32_e32 v2, s0, v53
	s_add_u32 s0, s1, s5
	s_addc_u32 s1, s6, 0
	v_lshlrev_b32_e32 v2, 2, v2
	global_load_ushort v36, v48, s[0:1]
	s_add_u32 s6, s0, 0x3800
	global_load_dword v2, v2, s[24:25]
	s_addc_u32 s7, s1, 0
	global_load_ushort v38, v50, s[0:1]
	global_load_ushort v37, v48, s[6:7]
	global_load_ushort v39, v50, s[6:7]
	s_add_u32 s6, s0, 0x7000
	s_addc_u32 s7, s1, 0
	global_load_ushort v94, v48, s[6:7]
	global_load_ushort v40, v50, s[6:7]
	s_add_u32 s6, s0, 0xa800
	s_addc_u32 s7, s1, 0
	global_load_ushort v100, v48, s[6:7]
	global_load_ushort v41, v50, s[6:7]
	s_add_u32 s6, s0, 0xe000
	s_addc_u32 s7, s1, 0
	global_load_ushort v101, v48, s[6:7]
	global_load_ushort v42, v50, s[6:7]
	s_add_u32 s6, s0, 0x11800
	s_addc_u32 s7, s1, 0
	global_load_ushort v105, v48, s[6:7]
	global_load_ushort v43, v50, s[6:7]
	s_add_u32 s6, s0, 0x15000
	s_addc_u32 s7, s1, 0
	global_load_ushort v106, v48, s[6:7]
	global_load_ushort v44, v50, s[6:7]
	s_add_u32 s6, s0, 0x18800
	s_addc_u32 s7, s1, 0
	global_load_ushort v111, v48, s[6:7]
	global_load_ushort v45, v50, s[6:7]
	s_add_u32 s6, s0, 0x1c000
	s_addc_u32 s7, s1, 0
	global_load_ushort v113, v48, s[6:7]
	global_load_ushort v46, v50, s[6:7]
	s_add_u32 s6, s0, 0x1f800
	s_addc_u32 s7, s1, 0
	global_load_ushort v115, v48, s[6:7]
	global_load_ushort v47, v50, s[6:7]
	s_add_u32 s6, s0, 0x23000
	s_addc_u32 s7, s1, 0
	global_load_ushort v118, v48, s[6:7]
	global_load_ushort v63, v50, s[6:7]
	s_add_u32 s6, s0, 0x26800
	s_addc_u32 s7, s1, 0
	global_load_ushort v122, v48, s[6:7]
	global_load_ushort v64, v50, s[6:7]
	s_add_u32 s6, s0, 0x2a000
	s_addc_u32 s7, s1, 0
	global_load_ushort v123, v48, s[6:7]
	global_load_ushort v65, v50, s[6:7]
	s_add_u32 s6, s0, 0x2d800
	s_addc_u32 s7, s1, 0
	global_load_ushort v125, v48, s[6:7]
	global_load_ushort v66, v50, s[6:7]
	s_add_u32 s6, s0, 0x31000
	s_addc_u32 s7, s1, 0
	global_load_ushort v126, v48, s[6:7]
	global_load_ushort v67, v50, s[6:7]
	s_add_u32 s6, s0, 0x34800
	s_addc_u32 s7, s1, 0
	global_load_ushort v131, v48, s[6:7]
	global_load_ushort v68, v50, s[6:7]
	s_add_u32 s6, s0, 0x38000
	s_addc_u32 s7, s1, 0
	global_load_ushort v132, v48, s[6:7]
	global_load_ushort v69, v50, s[6:7]
	s_add_u32 s6, s0, 0x3b800
	s_addc_u32 s7, s1, 0
	global_load_ushort v133, v48, s[6:7]
	global_load_ushort v71, v50, s[6:7]
	s_add_u32 s6, s0, 0x3f000
	s_addc_u32 s7, s1, 0
	global_load_ushort v135, v48, s[6:7]
	global_load_ushort v73, v50, s[6:7]
	s_add_u32 s6, s0, 0x42800
	s_addc_u32 s7, s1, 0
	global_load_ushort v139, v48, s[6:7]
	global_load_ushort v77, v50, s[6:7]
	s_add_u32 s6, s0, 0x46000
	s_addc_u32 s7, s1, 0
	global_load_ushort v140, v48, s[6:7]
	global_load_ushort v79, v50, s[6:7]
	s_add_u32 s6, s0, 0x49800
	s_addc_u32 s7, s1, 0
	global_load_ushort v142, v48, s[6:7]
	global_load_ushort v83, v50, s[6:7]
	s_add_u32 s6, s0, 0x4d000
	s_addc_u32 s7, s1, 0
	global_load_ushort v143, v48, s[6:7]
	global_load_ushort v84, v50, s[6:7]
	s_add_u32 s6, s0, 0x50800
	s_addc_u32 s7, s1, 0
	global_load_ushort v148, v48, s[6:7]
	global_load_ushort v88, v50, s[6:7]
	s_add_u32 s6, s0, 0x54000
	s_addc_u32 s7, s1, 0
	global_load_ushort v149, v48, s[6:7]
	global_load_ushort v89, v50, s[6:7]
	s_add_u32 s6, s0, 0x57800
	s_addc_u32 s7, s1, 0
	global_load_ushort v150, v48, s[6:7]
	global_load_ushort v91, v50, s[6:7]
	s_add_u32 s6, s0, 0x5b000
	s_addc_u32 s7, s1, 0
	global_load_ushort v153, v48, s[6:7]
	global_load_ushort v96, v50, s[6:7]
	s_add_u32 s6, s0, 0x5e800
	s_addc_u32 s7, s1, 0
	global_load_ushort v155, v48, s[6:7]
	global_load_ushort v98, v50, s[6:7]
	s_add_u32 s6, s0, 0x62000
	s_addc_u32 s7, s1, 0
	global_load_ushort v156, v48, s[6:7]
	global_load_ushort v102, v50, s[6:7]
	s_add_u32 s6, s0, 0x65800
	s_addc_u32 s7, s1, 0
	global_load_ushort v159, v48, s[6:7]
	global_load_ushort v108, v50, s[6:7]
	s_add_u32 s6, s0, 0x69000
	s_addc_u32 s7, s1, 0
	global_load_ushort v162, v48, s[6:7]
	s_add_u32 s0, s0, 0x6c800
	global_load_ushort v110, v50, s[6:7]
	s_addc_u32 s1, s1, 0
	global_load_ushort v164, v48, s[0:1]
	global_load_ushort v117, v50, s[0:1]
	s_add_u32 s5, s37, s5
	v_mov_b32_e32 v4, 0
	v_mov_b32_e32 v61, 1.0
	s_waitcnt vmcnt(62)
	v_sub_f32_e32 v62, 1.0, v2
	s_addc_u32 s6, s46, 0
	s_mov_b32 s7, 0
	v_mov_b32_e32 v5, v4
	v_mov_b32_e32 v6, v4
	v_mov_b32_e32 v7, v4
	v_mov_b32_e32 v8, v4
	v_mov_b32_e32 v9, v4
	v_mov_b32_e32 v10, v4
	v_mov_b32_e32 v11, v4
	v_mov_b32_e32 v12, v4
	v_mov_b32_e32 v13, v4
	v_mov_b32_e32 v14, v4
	v_mov_b32_e32 v15, v4
	v_mov_b32_e32 v16, v4
	v_mov_b32_e32 v17, v4
	v_mov_b32_e32 v18, v4
	v_mov_b32_e32 v19, v4
	v_mov_b32_e32 v20, v4
	v_mov_b32_e32 v21, v4
	v_mov_b32_e32 v22, v4
	v_mov_b32_e32 v23, v4
	v_mov_b32_e32 v24, v4
	v_mov_b32_e32 v25, v4
	v_mov_b32_e32 v26, v4
	v_mov_b32_e32 v27, v4
	v_mov_b32_e32 v28, v4
	v_mov_b32_e32 v29, v4
	v_mov_b32_e32 v30, v4
	v_mov_b32_e32 v31, v4
	v_mov_b32_e32 v32, v4
	v_mov_b32_e32 v33, v4
	v_mov_b32_e32 v34, v4
	v_mov_b32_e32 v35, v4
	v_mov_b32_e32 v70, v38
	s_waitcnt vmcnt(60)
	v_mov_b32_e32 v72, v39
	s_waitcnt vmcnt(58)
	v_mov_b32_e32 v75, v40
	s_waitcnt vmcnt(56)
	v_mov_b32_e32 v80, v41
	s_waitcnt vmcnt(54)
	v_mov_b32_e32 v82, v42
	s_waitcnt vmcnt(52)
	v_mov_b32_e32 v85, v43
	s_waitcnt vmcnt(50)
	v_mov_b32_e32 v87, v44
	s_waitcnt vmcnt(48)
	v_mov_b32_e32 v93, v45
	s_waitcnt vmcnt(46)
	v_mov_b32_e32 v97, v46
	s_waitcnt vmcnt(44)
	v_mov_b32_e32 v99, v47
	s_waitcnt vmcnt(42)
	v_mov_b32_e32 v104, v63
	s_waitcnt vmcnt(40)
	v_mov_b32_e32 v112, v64
	s_waitcnt vmcnt(38)
	v_mov_b32_e32 v116, v65
	s_waitcnt vmcnt(36)
	v_mov_b32_e32 v119, v66
	s_waitcnt vmcnt(34)
	v_mov_b32_e32 v121, v67
	s_waitcnt vmcnt(32)
	v_mov_b32_e32 v128, v68
	s_waitcnt vmcnt(30)
	v_mov_b32_e32 v130, v69
	s_waitcnt vmcnt(28)
	v_mov_b32_e32 v134, v71
	s_waitcnt vmcnt(26)
	v_mov_b32_e32 v137, v73
	s_waitcnt vmcnt(24)
	v_mov_b32_e32 v144, v77
	s_waitcnt vmcnt(22)
	v_mov_b32_e32 v146, v79
	s_waitcnt vmcnt(20)
	v_mov_b32_e32 v147, v83
	s_waitcnt vmcnt(18)
	v_mov_b32_e32 v152, v84
	s_waitcnt vmcnt(16)
	v_mov_b32_e32 v158, v88
	s_waitcnt vmcnt(14)
	v_mov_b32_e32 v161, v89
	s_waitcnt vmcnt(12)
	v_mov_b32_e32 v163, v91
	s_waitcnt vmcnt(10)
	v_mov_b32_e32 v166, v96
	s_waitcnt vmcnt(8)
	v_mov_b32_e32 v169, v98
	s_waitcnt vmcnt(6)
	v_mov_b32_e32 v171, v102
	v_mov_b32_e32 v74, v36
	v_mov_b32_e32 v76, v37
	v_mov_b32_e32 v78, v94
	s_waitcnt vmcnt(4)
	v_mov_b32_e32 v172, v108
	v_mov_b32_e32 v81, v100
	v_mov_b32_e32 v86, v101
	v_mov_b32_e32 v90, v105
	v_mov_b32_e32 v92, v106
	v_mov_b32_e32 v95, v111
	s_waitcnt vmcnt(2)
	v_mov_b32_e32 v174, v110
	v_mov_b32_e32 v103, v113
	v_mov_b32_e32 v107, v115
	v_mov_b32_e32 v109, v118
	s_waitcnt vmcnt(0)
	v_mov_b32_e32 v177, v117
	v_mov_b32_e32 v114, v122
	v_mov_b32_e32 v120, v123
	v_mov_b32_e32 v124, v125
	v_mov_b32_e32 v127, v126
	v_mov_b32_e32 v129, v131
	v_mov_b32_e32 v136, v132
	v_mov_b32_e32 v138, v133
	v_mov_b32_e32 v141, v135
	v_mov_b32_e32 v145, v139
	v_mov_b32_e32 v151, v140
	v_mov_b32_e32 v154, v142
	v_mov_b32_e32 v157, v143
	v_mov_b32_e32 v160, v148
	v_mov_b32_e32 v165, v149
	v_mov_b32_e32 v167, v150
	v_mov_b32_e32 v168, v153
	v_mov_b32_e32 v170, v155
	v_mov_b32_e32 v173, v156
	v_mov_b32_e32 v175, v159
	v_mov_b32_e32 v176, v162
	v_mov_b32_e32 v178, v164
	s_cmpk_eq_i32 s7, 0x180
	s_cbranch_scc1 .LBB0_445
.LBB0_444:
	s_add_i32 s0, s4, s7
	s_mul_hi_i32 s1, s0, 0x3800
	s_mulk_i32 s0, 0x3800
	s_add_u32 s0, s5, s0
	s_addc_u32 s1, s6, s1
	s_add_u32 s8, s0, 0x3800
	global_load_ushort v74, v48, s[0:1]
	global_load_ushort v70, v50, s[0:1]
	s_addc_u32 s9, s1, 0
	s_nop 0
	global_load_ushort v76, v48, s[8:9]
	global_load_ushort v72, v50, s[8:9]
	s_add_u32 s8, s0, 0x7000
	s_addc_u32 s9, s1, 0
	global_load_ushort v78, v48, s[8:9]
	global_load_ushort v75, v50, s[8:9]
	s_add_u32 s8, s0, 0xa800
	s_addc_u32 s9, s1, 0
	global_load_ushort v81, v48, s[8:9]
	v_lshl_add_u64 v[86:87], s[8:9], 0, v[50:51]
	s_add_u32 s8, s0, 0xe000
	s_addc_u32 s9, s1, 0
	global_load_ushort v82, v50, s[8:9]
	s_nop 0
	global_load_ushort v80, v[86:87], off
	global_load_ushort v86, v48, s[8:9]
	s_add_u32 s8, s0, 0x11800
	s_addc_u32 s9, s1, 0
	global_load_ushort v90, v48, s[8:9]
	s_nop 0
	global_load_ushort v85, v50, s[8:9]
	s_add_u32 s8, s0, 0x15000
	s_addc_u32 s9, s1, 0
	global_load_ushort v87, v50, s[8:9]
	global_load_ushort v92, v48, s[8:9]
	s_add_u32 s8, s0, 0x18800
	s_addc_u32 s9, s1, 0
	global_load_ushort v95, v48, s[8:9]
	s_nop 0
	global_load_ushort v93, v50, s[8:9]
	s_add_u32 s8, s0, 0x1c000
	s_addc_u32 s9, s1, 0
	global_load_ushort v103, v48, s[8:9]
	global_load_ushort v97, v50, s[8:9]
	s_add_u32 s8, s0, 0x1f800
	s_addc_u32 s9, s1, 0
	global_load_ushort v107, v48, s[8:9]
	global_load_ushort v99, v50, s[8:9]
	s_add_u32 s8, s0, 0x23000
	s_addc_u32 s9, s1, 0
	global_load_ushort v109, v48, s[8:9]
	global_load_ushort v104, v50, s[8:9]
	s_add_u32 s8, s0, 0x26800
	s_addc_u32 s9, s1, 0
	global_load_ushort v114, v48, s[8:9]
	global_load_ushort v112, v50, s[8:9]
	s_add_u32 s8, s0, 0x2a000
	s_addc_u32 s9, s1, 0
	global_load_ushort v116, v50, s[8:9]
	global_load_ushort v120, v48, s[8:9]
	s_add_u32 s8, s0, 0x2d800
	s_addc_u32 s9, s1, 0
	global_load_ushort v124, v48, s[8:9]
	s_nop 0
	global_load_ushort v119, v50, s[8:9]
	s_add_u32 s8, s0, 0x31000
	s_addc_u32 s9, s1, 0
	global_load_ushort v127, v48, s[8:9]
	global_load_ushort v121, v50, s[8:9]
	s_add_u32 s8, s0, 0x34800
	s_addc_u32 s9, s1, 0
	global_load_ushort v129, v48, s[8:9]
	v_lshl_add_u64 v[136:137], s[8:9], 0, v[50:51]
	s_add_u32 s8, s0, 0x38000
	s_addc_u32 s9, s1, 0
	global_load_ushort v130, v50, s[8:9]
	s_nop 0
	global_load_ushort v128, v[136:137], off
	global_load_ushort v136, v48, s[8:9]
	s_add_u32 s8, s0, 0x3b800
	s_addc_u32 s9, s1, 0
	global_load_ushort v138, v48, s[8:9]
	s_nop 0
	global_load_ushort v134, v50, s[8:9]
	s_add_u32 s8, s0, 0x3f000
	s_addc_u32 s9, s1, 0
	global_load_ushort v141, v48, s[8:9]
	global_load_ushort v137, v50, s[8:9]
	s_add_u32 s8, s0, 0x42800
	s_addc_u32 s9, s1, 0
	global_load_ushort v145, v48, s[8:9]
	global_load_ushort v144, v50, s[8:9]
	s_add_u32 s8, s0, 0x46000
	s_addc_u32 s9, s1, 0
	s_nop 0
	global_load_ushort v151, v48, s[8:9]
	global_load_ushort v146, v50, s[8:9]
	s_add_u32 s8, s0, 0x49800
	s_addc_u32 s9, s1, 0
	global_load_ushort v154, v48, s[8:9]
	s_nop 0
	global_load_ushort v147, v50, s[8:9]
	s_add_u32 s8, s0, 0x4d000
	s_addc_u32 s9, s1, 0
	global_load_ushort v157, v48, s[8:9]
	global_load_ushort v152, v50, s[8:9]
	s_add_u32 s8, s0, 0x50800
	s_addc_u32 s9, s1, 0
	global_load_ushort v158, v50, s[8:9]
	global_load_ushort v160, v48, s[8:9]
	s_add_u32 s8, s0, 0x54000
	s_addc_u32 s9, s1, 0
	global_load_ushort v165, v48, s[8:9]
	s_nop 0
	global_load_ushort v161, v50, s[8:9]
	s_add_u32 s8, s0, 0x57800
	s_addc_u32 s9, s1, 0
	global_load_ushort v163, v50, s[8:9]
	v_lshl_add_u64 v[166:167], s[8:9], 0, v[48:49]
	s_add_u32 s8, s0, 0x5b000
	s_addc_u32 s9, s1, 0
	v_lshl_add_u64 v[168:169], s[8:9], 0, v[48:49]
	v_lshl_add_u64 v[170:171], s[8:9], 0, v[50:51]
	s_add_u32 s8, s0, 0x5e800
	s_addc_u32 s9, s1, 0
	v_lshl_add_u64 v[172:173], s[8:9], 0, v[50:51]
	global_load_ushort v167, v[166:167], off
	s_nop 0
	global_load_ushort v168, v[168:169], off
	s_nop 0
	global_load_ushort v166, v[170:171], off
	global_load_ushort v169, v[172:173], off
	v_lshl_add_u64 v[170:171], s[8:9], 0, v[48:49]
	s_add_u32 s8, s0, 0x62000
	s_addc_u32 s9, s1, 0
	v_lshl_add_u64 v[172:173], s[8:9], 0, v[48:49]
	v_lshl_add_u64 v[174:175], s[8:9], 0, v[50:51]
	s_add_u32 s8, s0, 0x65800
	s_addc_u32 s9, s1, 0
	v_lshl_add_u64 v[176:177], s[8:9], 0, v[50:51]
	global_load_ushort v170, v[170:171], off
	s_nop 0
	global_load_ushort v173, v[172:173], off
	s_nop 0
	global_load_ushort v171, v[174:175], off
	global_load_ushort v172, v[176:177], off
	v_lshl_add_u64 v[174:175], s[8:9], 0, v[48:49]
	s_add_u32 s8, s0, 0x69000
	s_addc_u32 s9, s1, 0
	s_add_u32 s0, s0, 0x6c800
	s_addc_u32 s1, s1, 0
	global_load_ushort v176, v48, s[8:9]
	global_load_ushort v174, v50, s[8:9]
	global_load_ushort v177, v50, s[0:1]
	global_load_ushort v175, v[174:175], off
	s_nop 0
	s_nop 0
	global_load_ushort v178, v48, s[0:1]

.LBB0_638:
	s_and_b32 s7, s85, 15
	s_and_b32 s6, s1, 0xffffe000
	s_lshl_b32 s7, s7, 9
	s_or_b32 s83, s6, s7
	s_lshl_b32 s6, s82, 6
	s_and_b32 s6, s6, 0xffffe000
	s_lshl_b32 s5, s5, 9
	s_or_b32 s5, s6, s5
	s_lshl_b32 s72, s4, 2
	s_mul_hi_i32 s6, s5, 0x3800
	s_mulk_i32 s5, 0x3800
	s_add_u32 s5, s20, s5
	v_lshl_add_u64 v[28:29], v[104:105], 0, s[72:73]
	s_addc_u32 s6, s21, s6
	s_lshl_b32 s72, s4, 1
	s_add_u32 s54, s5, s72
	s_addc_u32 s55, s6, 0
	v_lshl_add_u64 v[24:25], s[24:25], 2, v[28:29]
	v_lshl_add_u64 v[64:65], s[54:55], 0, v[114:115]
	global_load_dwordx4 v[16:19], v[24:25], off
	global_load_dwordx4 v[20:23], v[24:25], off offset:64
	s_nop 0
	global_load_dwordx4 v[24:27], v[24:25], off offset:128
	s_add_u32 s6, s54, 0x3800
	global_load_ushort v168, v[64:65], off
	global_load_ushort v68, v116, s[54:55]
	global_load_ushort v226, v118, s[54:55]
	s_addc_u32 s7, s55, 0
	global_load_ushort v169, v114, s[6:7]
	global_load_ushort v69, v116, s[6:7]
	global_load_ushort v225, v118, s[6:7]
	s_add_u32 s6, s54, 0x7000
	s_addc_u32 s7, s55, 0
	global_load_ushort v170, v114, s[6:7]
	global_load_ushort v70, v116, s[6:7]
	global_load_ushort v223, v118, s[6:7]
	s_add_u32 s6, s54, 0xa800
	s_addc_u32 s7, s55, 0
	global_load_ushort v171, v114, s[6:7]
	global_load_ushort v71, v116, s[6:7]
	global_load_ushort v221, v118, s[6:7]
	s_add_u32 s6, s54, 0xe000
	s_addc_u32 s7, s55, 0
	global_load_ushort v172, v114, s[6:7]
	global_load_ushort v72, v116, s[6:7]
	global_load_ushort v219, v118, s[6:7]
	s_add_u32 s6, s54, 0x11800
	s_addc_u32 s7, s55, 0
	global_load_ushort v173, v114, s[6:7]
	global_load_ushort v73, v116, s[6:7]
	global_load_ushort v131, v118, s[6:7]
	s_add_u32 s6, s54, 0x15000
	s_addc_u32 s7, s55, 0
	global_load_ushort v174, v114, s[6:7]
	global_load_ushort v74, v116, s[6:7]
	global_load_ushort v129, v118, s[6:7]
	s_add_u32 s6, s54, 0x18800
	s_addc_u32 s7, s55, 0
	global_load_ushort v175, v114, s[6:7]
	global_load_ushort v75, v116, s[6:7]
	global_load_ushort v128, v118, s[6:7]
	s_add_u32 s6, s54, 0x1c000
	s_addc_u32 s7, s55, 0
	global_load_ushort v178, v114, s[6:7]
	global_load_ushort v76, v116, s[6:7]
	global_load_ushort v125, v118, s[6:7]
	s_add_u32 s6, s54, 0x1f800
	s_addc_u32 s7, s55, 0
	global_load_ushort v179, v114, s[6:7]
	global_load_ushort v77, v116, s[6:7]
	global_load_ushort v124, v118, s[6:7]
	s_add_u32 s6, s54, 0x23000
	s_addc_u32 s7, s55, 0
	global_load_ushort v180, v114, s[6:7]
	global_load_ushort v78, v116, s[6:7]
	global_load_ushort v103, v118, s[6:7]
	s_add_u32 s6, s54, 0x26800
	s_addc_u32 s7, s55, 0
	global_load_ushort v181, v114, s[6:7]
	global_load_ushort v79, v116, s[6:7]
	global_load_ushort v101, v118, s[6:7]
	s_add_u32 s6, s54, 0x2a000
	s_addc_u32 s7, s55, 0
	global_load_ushort v182, v114, s[6:7]
	global_load_ushort v80, v116, s[6:7]
	global_load_ushort v98, v118, s[6:7]
	s_add_u32 s6, s54, 0x2d800
	s_addc_u32 s7, s55, 0
	global_load_ushort v183, v114, s[6:7]
	global_load_ushort v81, v116, s[6:7]
	global_load_ushort v96, v118, s[6:7]
	s_add_u32 s6, s54, 0x31000
	s_addc_u32 s7, s55, 0
	global_load_ushort v184, v114, s[6:7]
	global_load_ushort v82, v116, s[6:7]
	global_load_ushort v94, v118, s[6:7]
	s_add_u32 s6, s54, 0x34800
	s_addc_u32 s7, s55, 0
	global_load_ushort v185, v114, s[6:7]
	global_load_ushort v83, v116, s[6:7]
	v_lshl_add_u64 v[28:29], s[60:61], 2, v[28:29]
	global_load_ushort v92, v118, s[6:7]
	global_load_dwordx4 v[28:31], v[28:29], off
	s_add_u32 s89, s20, s72
	v_or_b32_e32 v166, s83, v147
	v_or_b32_e32 v167, s83, v140
	s_waitcnt vmcnt(52)
	v_sub_f32_e32 v176, 1.0, v165
	s_addc_u32 s90, s21, 0
	v_lshl_add_u64 v[120:121], v[112:113], 0, s[72:73]
	s_mov_b32 s91, 0
	s_lshl_b32 s72, s4, 1
	v_mov_b32_e32 v177, v133

.LBB0_643:
	s_or_b64 exec, exec, s[54:55]
	s_cmpk_eq_i32 s91, 0x1c0
	v_mov_b32_e32 v187, v226
	v_mov_b32_e32 v189, v225
	v_mov_b32_e32 v191, v223
	v_mov_b32_e32 v193, v221
	v_mov_b32_e32 v195, v219
	v_mov_b32_e32 v197, v131
	v_mov_b32_e32 v199, v129
	v_mov_b32_e32 v201, v128
	v_mov_b32_e32 v203, v125
	v_mov_b32_e32 v205, v124
	v_mov_b32_e32 v207, v103
	v_mov_b32_e32 v209, v101
	v_mov_b32_e32 v211, v98
	v_mov_b32_e32 v213, v96
	v_mov_b32_e32 v215, v94
	s_waitcnt vmcnt(0)
	v_mov_b32_e32 v217, v92
	v_mov_b32_e32 v186, v68
	v_mov_b32_e32 v188, v69
	v_mov_b32_e32 v190, v70
	v_mov_b32_e32 v192, v71
	v_mov_b32_e32 v194, v72
	v_mov_b32_e32 v196, v73
	v_mov_b32_e32 v198, v74
	v_mov_b32_e32 v200, v75
	v_mov_b32_e32 v202, v76
	v_mov_b32_e32 v204, v77
	v_mov_b32_e32 v206, v78
	v_mov_b32_e32 v208, v79
	v_mov_b32_e32 v210, v80
	v_mov_b32_e32 v212, v81
	v_mov_b32_e32 v214, v82
	v_mov_b32_e32 v216, v83
	ds_write_b32 v134, v64
	s_cbranch_scc1 .LBB0_645
	s_add_i32 s4, s83, s91
	s_add_i32 s4, s4, 64
	s_mul_hi_i32 s5, s4, 0x3800
	s_mulk_i32 s4, 0x3800
	s_add_u32 s54, s89, s4
	s_addc_u32 s55, s90, s5
	global_load_ushort v168, v114, s[54:55]
	global_load_ushort v186, v116, s[54:55]
	s_add_u32 s4, s54, 0x3800
	global_load_ushort v187, v118, s[54:55]
	s_addc_u32 s5, s55, 0
	global_load_ushort v169, v114, s[4:5]
	global_load_ushort v188, v116, s[4:5]
	global_load_ushort v189, v118, s[4:5]
	s_add_u32 s4, s54, 0x7000
	s_addc_u32 s5, s55, 0
	global_load_ushort v170, v114, s[4:5]
	global_load_ushort v190, v116, s[4:5]
	global_load_ushort v191, v118, s[4:5]
	s_add_u32 s4, s54, 0xa800
	s_addc_u32 s5, s55, 0
	global_load_ushort v171, v114, s[4:5]
	global_load_ushort v192, v116, s[4:5]
	global_load_ushort v193, v118, s[4:5]
	s_add_u32 s4, s54, 0xe000
	s_addc_u32 s5, s55, 0
	global_load_ushort v172, v114, s[4:5]
	global_load_ushort v194, v116, s[4:5]
	global_load_ushort v195, v118, s[4:5]
	s_add_u32 s4, s54, 0x11800
	s_addc_u32 s5, s55, 0
	global_load_ushort v173, v114, s[4:5]
	global_load_ushort v196, v116, s[4:5]
	global_load_ushort v197, v118, s[4:5]
	s_add_u32 s4, s54, 0x15000
	s_addc_u32 s5, s55, 0
	global_load_ushort v174, v114, s[4:5]
	global_load_ushort v198, v116, s[4:5]
	global_load_ushort v199, v118, s[4:5]
	s_add_u32 s4, s54, 0x18800
	s_addc_u32 s5, s55, 0
	global_load_ushort v175, v114, s[4:5]
	global_load_ushort v200, v116, s[4:5]
	global_load_ushort v201, v118, s[4:5]
	s_add_u32 s4, s54, 0x1c000
	s_addc_u32 s5, s55, 0
	global_load_ushort v178, v114, s[4:5]
	global_load_ushort v202, v116, s[4:5]
	global_load_ushort v203, v118, s[4:5]
	s_add_u32 s4, s54, 0x1f800
	s_addc_u32 s5, s55, 0
	global_load_ushort v179, v114, s[4:5]
	global_load_ushort v204, v116, s[4:5]
	global_load_ushort v205, v118, s[4:5]
	s_add_u32 s4, s54, 0x23000
	s_addc_u32 s5, s55, 0
	global_load_ushort v180, v114, s[4:5]
	global_load_ushort v206, v116, s[4:5]
	global_load_ushort v207, v118, s[4:5]
	s_add_u32 s4, s54, 0x26800
	s_addc_u32 s5, s55, 0
	global_load_ushort v181, v114, s[4:5]
	global_load_ushort v208, v116, s[4:5]
	global_load_ushort v209, v118, s[4:5]
	s_add_u32 s4, s54, 0x2a000
	s_addc_u32 s5, s55, 0
	global_load_ushort v182, v114, s[4:5]
	global_load_ushort v210, v116, s[4:5]
	global_load_ushort v211, v118, s[4:5]
	s_add_u32 s4, s54, 0x2d800
	s_addc_u32 s5, s55, 0
	global_load_ushort v183, v114, s[4:5]
	global_load_ushort v212, v116, s[4:5]
	global_load_ushort v213, v118, s[4:5]
	s_add_u32 s4, s54, 0x31000
	s_addc_u32 s5, s55, 0
	global_load_ushort v184, v114, s[4:5]
	global_load_ushort v214, v116, s[4:5]
	global_load_ushort v215, v118, s[4:5]
	s_add_u32 s4, s54, 0x34800
	s_addc_u32 s5, s55, 0
	global_load_ushort v185, v114, s[4:5]
	global_load_ushort v216, v116, s[4:5]
	global_load_ushort v217, v118, s[4:5]

.LBB0_649:
	s_or_b64 exec, exec, s[56:57]
	s_waitcnt lgkmcnt(0)
	v_cndmask_b32_e64 v67, 1.0, v67, s[42:43]
	v_cndmask_b32_e64 v66, v67, v66, s[40:41]
	v_lshlrev_b32_e32 v67, 16, v226
	v_mul_f32_e32 v226, 0xbfb8aa3b, v67
	v_exp_f32_e32 v226, v226
	v_lshlrev_b32_e32 v225, 16, v225
	v_lshlrev_b32_e32 v223, 16, v223
	v_lshlrev_b32_e32 v221, 16, v221
	v_add_f32_e32 v226, 1.0, v226
	v_rcp_f32_e32 v238, v226
	v_lshlrev_b32_e32 v219, 16, v219
	v_lshlrev_b32_e32 v131, 16, v131
	v_lshlrev_b32_e32 v129, 16, v129
	v_mul_f32_e32 v67, v67, v238
	v_mul_f32_e32 v238, 0xbfb8aa3b, v225
	v_exp_f32_e32 v238, v238
	v_sub_f32_e32 v226, 1.0, v245
	v_lshlrev_b32_e32 v128, 16, v128
	v_lshlrev_b32_e32 v125, 16, v125
	v_add_f32_e32 v238, 1.0, v238
	v_rcp_f32_e32 v239, v238
	v_lshlrev_b32_e32 v124, 16, v124
	v_lshlrev_b32_e32 v103, 16, v103
	v_lshlrev_b32_e32 v101, 16, v101
	v_mul_f32_e32 v225, v225, v239
	v_mul_f32_e32 v238, 0xbfb8aa3b, v223
	v_exp_f32_e32 v238, v238
	v_lshlrev_b32_e32 v98, 16, v98
	v_lshlrev_b32_e32 v96, 16, v96
	v_lshlrev_b32_e32 v94, 16, v94
	v_add_f32_e32 v238, 1.0, v238
	v_rcp_f32_e32 v239, v238
	v_lshlrev_b32_e32 v92, 16, v92
	v_mul_f32_e32 v126, v126, v66
	v_mul_f32_e32 v122, v122, v66
	v_mul_f32_e32 v223, v223, v239
	v_mul_f32_e32 v238, 0xbfb8aa3b, v221
	v_exp_f32_e32 v238, v238
	v_mul_f32_e32 v102, v102, v66
	v_sub_f32_e32 v243, 1.0, v243
	v_sub_f32_e32 v244, 1.0, v244
	v_add_f32_e32 v238, 1.0, v238
	v_rcp_f32_e32 v239, v238
	v_mul_f32_e32 v100, v100, v66
	v_mul_f32_e32 v99, v99, v66
	v_sub_f32_e32 v242, 1.0, v242
	v_mul_f32_e32 v221, v221, v239
	v_mul_f32_e32 v238, 0xbfb8aa3b, v219
	v_exp_f32_e32 v238, v238
	v_sub_f32_e32 v231, 1.0, v231
	v_mul_f32_e32 v97, v97, v66
	v_mul_f32_e32 v95, v95, v66
	v_add_f32_e32 v238, 1.0, v238
	v_rcp_f32_e32 v239, v238
	v_sub_f32_e32 v230, 1.0, v230
	v_sub_f32_e32 v229, 1.0, v229
	v_mul_f32_e32 v93, v93, v66
	v_mul_f32_e32 v219, v219, v239
	v_mul_f32_e32 v238, 0xbfb8aa3b, v131
	v_exp_f32_e32 v238, v238
	v_mul_f32_e32 v91, v91, v66
	v_sub_f32_e32 v228, 1.0, v228
	v_sub_f32_e32 v227, 1.0, v227
	v_add_f32_e32 v238, 1.0, v238
	v_rcp_f32_e32 v239, v238
	v_mul_f32_e32 v90, v90, v66
	v_mul_f32_e32 v89, v89, v66
	v_sub_f32_e32 v224, 1.0, v224
	v_mul_f32_e32 v131, v131, v239
	v_mul_f32_e32 v238, 0xbfb8aa3b, v129
	v_exp_f32_e32 v238, v238
	v_sub_f32_e32 v222, 1.0, v222
	v_mul_f32_e32 v88, v88, v66
	v_mul_f32_e32 v87, v87, v66
	v_add_f32_e32 v238, 1.0, v238
	v_rcp_f32_e32 v239, v238
	v_sub_f32_e32 v220, 1.0, v220
	v_sub_f32_e32 v218, 1.0, v218
	v_mul_f32_e32 v86, v86, v66
	v_mul_f32_e32 v129, v129, v239
	v_mul_f32_e32 v238, 0xbfb8aa3b, v128
	v_exp_f32_e32 v238, v238
	v_mul_f32_e32 v85, v85, v66
	v_mul_f32_e32 v66, v84, v66
	v_max_f32_e32 v84, 0x5bf68a9, v66
	v_add_f32_e32 v238, 1.0, v238
	v_rcp_f32_e32 v239, v238
	v_rcp_f32_e32 v84, v84
	v_sub_f32_e32 v130, 1.0, v130
	v_sub_f32_e32 v127, 1.0, v127
	v_mul_f32_e32 v128, v128, v239
	v_mul_f32_e32 v238, 0xbfb8aa3b, v125
	v_exp_f32_e32 v238, v238
	v_sub_f32_e32 v123, 1.0, v123
	v_lshl_or_b32 v68, v69, 16, v68
	v_lshl_or_b32 v69, v71, 16, v70
	v_add_f32_e32 v238, 1.0, v238
	v_rcp_f32_e32 v239, v238
	v_lshl_or_b32 v72, v73, 16, v72
	v_lshl_or_b32 v73, v75, 16, v74
	v_add_u32_e32 v74, 0x8800, v149
	v_mul_f32_e32 v125, v125, v239
	v_mul_f32_e32 v238, 0xbfb8aa3b, v124
	v_exp_f32_e32 v238, v238
	v_add_u32_e32 v75, 0xd000, v149
	v_add_f32_e32 v238, 1.0, v238
	v_rcp_f32_e32 v239, v238
	s_nop 0
	v_mul_f32_e32 v124, v124, v239
	v_mul_f32_e32 v238, 0xbfb8aa3b, v103
	v_exp_f32_e32 v238, v238
	s_nop 0
	v_add_f32_e32 v238, 1.0, v238
	v_rcp_f32_e32 v239, v238
	s_nop 0
	v_mul_f32_e32 v103, v103, v239
	v_mul_f32_e32 v238, 0xbfb8aa3b, v101
	v_exp_f32_e32 v238, v238
	s_nop 0
	v_add_f32_e32 v238, 1.0, v238
	v_rcp_f32_e32 v239, v238
	s_nop 0
	v_mul_f32_e32 v101, v101, v239
	v_mul_f32_e32 v238, 0xbfb8aa3b, v98
	v_exp_f32_e32 v238, v238
	s_nop 0
	v_add_f32_e32 v238, 1.0, v238
	v_rcp_f32_e32 v239, v238
	s_nop 0
	v_mul_f32_e32 v98, v98, v239
	v_mul_f32_e32 v238, 0xbfb8aa3b, v96
	v_exp_f32_e32 v238, v238
	s_nop 0
	v_add_f32_e32 v238, 1.0, v238
	v_rcp_f32_e32 v239, v238
	s_nop 0
	v_mul_f32_e32 v96, v96, v239
	v_mul_f32_e32 v238, 0xbfb8aa3b, v94
	v_exp_f32_e32 v238, v238
	s_nop 0
	v_add_f32_e32 v238, 1.0, v238
	v_rcp_f32_e32 v239, v238
	s_nop 0
	v_mul_f32_e32 v94, v94, v239
	v_mul_f32_e32 v238, 0xbfb8aa3b, v92
	v_exp_f32_e32 v238, v238
	s_nop 0
	v_add_f32_e32 v238, 1.0, v238
	v_rcp_f32_e32 v239, v238
	s_nop 0
	v_mul_f32_e32 v92, v92, v239
	v_max_f32_e32 v238, 0x5bf68a9, v126
	v_rcp_f32_e32 v238, v238
	s_nop 0
	v_cndmask_b32_e64 v239, v238, v126, s[36:37]
	v_cndmask_b32_e64 v126, v126, v238, s[36:37]
	v_mul_f32_e32 v226, v226, v239
	v_mul_f32_e32 v67, v67, v126
	v_cvt_pk_bf16_f32 v126, v226, v67
	ds_write_b16 v148, v126 offset:17408
	ds_write_b16_d16_hi v148, v126
	v_and_b32_e32 v67, 0xffff, v126
	v_max_f32_e32 v126, 0x5bf68a9, v122
	v_rcp_f32_e32 v126, v126
	s_nop 0
	v_cndmask_b32_e64 v226, v126, v122, s[36:37]
	v_cndmask_b32_e64 v122, v122, v126, s[36:37]
	v_max_f32_e32 v126, 0x5bf68a9, v102
	v_rcp_f32_e32 v126, v126
	v_mul_f32_e32 v122, v225, v122
	v_mul_f32_e32 v226, v243, v226
	v_cvt_pk_bf16_f32 v122, v226, v122
	v_cndmask_b32_e64 v225, v126, v102, s[36:37]
	v_cndmask_b32_e64 v102, v102, v126, s[36:37]
	v_mul_f32_e32 v102, v223, v102
	ds_write_b16 v148, v122 offset:17680
	ds_write_b16_d16_hi v148, v122 offset:272
	v_mul_f32_e32 v225, v244, v225
	v_cvt_pk_bf16_f32 v102, v225, v102
	ds_write_b16 v148, v102 offset:17952
	ds_write_b16_d16_hi v148, v102 offset:544
	v_and_b32_e32 v126, 0xffff, v102
	v_max_f32_e32 v102, 0x5bf68a9, v100
	v_rcp_f32_e32 v102, v102
	s_nop 0
	v_cndmask_b32_e64 v223, v102, v100, s[36:37]
	v_cndmask_b32_e64 v100, v100, v102, s[36:37]
	v_max_f32_e32 v102, 0x5bf68a9, v99
	v_rcp_f32_e32 v102, v102
	v_mul_f32_e32 v100, v221, v100
	v_mul_f32_e32 v223, v242, v223
	v_cvt_pk_bf16_f32 v100, v223, v100
	v_cndmask_b32_e64 v221, v102, v99, s[36:37]
	v_cndmask_b32_e64 v99, v99, v102, s[36:37]
	v_mul_f32_e32 v99, v219, v99
	ds_write_b16 v148, v100 offset:18224
	ds_write_b16_d16_hi v148, v100 offset:816
	v_mul_f32_e32 v221, v231, v221
	v_cvt_pk_bf16_f32 v99, v221, v99
	ds_write_b16 v148, v99 offset:18496
	ds_write_b16_d16_hi v148, v99 offset:1088
	v_and_b32_e32 v102, 0xffff, v99
	v_max_f32_e32 v99, 0x5bf68a9, v97
	v_rcp_f32_e32 v99, v99
	s_nop 0
	v_cndmask_b32_e64 v219, v99, v97, s[36:37]
	v_cndmask_b32_e64 v97, v97, v99, s[36:37]
	v_max_f32_e32 v99, 0x5bf68a9, v95
	v_rcp_f32_e32 v99, v99
	v_mul_f32_e32 v97, v131, v97
	v_mul_f32_e32 v219, v230, v219
	v_cvt_pk_bf16_f32 v97, v219, v97
	v_cndmask_b32_e64 v131, v99, v95, s[36:37]
	v_cndmask_b32_e64 v95, v95, v99, s[36:37]
	v_mul_f32_e32 v95, v129, v95
	ds_write_b16 v148, v97 offset:18768
	ds_write_b16_d16_hi v148, v97 offset:1360
	v_mul_f32_e32 v131, v229, v131
	v_cvt_pk_bf16_f32 v95, v131, v95
	ds_write_b16 v148, v95 offset:19040
	ds_write_b16_d16_hi v148, v95 offset:1632
	v_and_b32_e32 v99, 0xffff, v95
	v_max_f32_e32 v95, 0x5bf68a9, v93
	v_rcp_f32_e32 v95, v95
	v_lshl_or_b32 v70, v97, 16, v102
	v_cndmask_b32_e64 v129, v95, v93, s[36:37]
	v_cndmask_b32_e64 v93, v93, v95, s[36:37]
	v_max_f32_e32 v95, 0x5bf68a9, v91
	v_rcp_f32_e32 v95, v95
	v_mul_f32_e32 v93, v128, v93
	v_mul_f32_e32 v129, v228, v129
	v_cvt_pk_bf16_f32 v93, v129, v93
	v_cndmask_b32_e64 v128, v95, v91, s[36:37]
	v_cndmask_b32_e64 v91, v91, v95, s[36:37]
	v_mul_f32_e32 v91, v125, v91
	ds_write_b16 v148, v93 offset:19312
	ds_write_b16_d16_hi v148, v93 offset:1904
	v_mul_f32_e32 v128, v227, v128
	v_cvt_pk_bf16_f32 v91, v128, v91
	ds_write_b16 v148, v91 offset:19584
	ds_write_b16_d16_hi v148, v91 offset:2176
	v_and_b32_e32 v95, 0xffff, v91
	v_max_f32_e32 v91, 0x5bf68a9, v90
	v_rcp_f32_e32 v91, v91
	v_lshl_or_b32 v71, v93, 16, v99
	v_cndmask_b32_e64 v125, v91, v90, s[36:37]
	v_cndmask_b32_e64 v90, v90, v91, s[36:37]
	v_max_f32_e32 v91, 0x5bf68a9, v89
	v_rcp_f32_e32 v91, v91
	v_mul_f32_e32 v90, v124, v90
	v_mul_f32_e32 v125, v224, v125
	v_cvt_pk_bf16_f32 v90, v125, v90
	v_cndmask_b32_e64 v124, v91, v89, s[36:37]
	v_cndmask_b32_e64 v89, v89, v91, s[36:37]
	v_mul_f32_e32 v89, v103, v89
	ds_write_b16 v148, v90 offset:19856
	ds_write_b16_d16_hi v148, v90 offset:2448
	v_mul_f32_e32 v124, v222, v124
	v_cvt_pk_bf16_f32 v89, v124, v89
	ds_write_b16 v148, v89 offset:20128
	ds_write_b16_d16_hi v148, v89 offset:2720
	v_and_b32_e32 v91, 0xffff, v89
	v_max_f32_e32 v89, 0x5bf68a9, v88
	v_rcp_f32_e32 v89, v89
	s_nop 0
	v_cndmask_b32_e64 v103, v89, v88, s[36:37]
	v_cndmask_b32_e64 v88, v88, v89, s[36:37]
	v_max_f32_e32 v89, 0x5bf68a9, v87
	v_rcp_f32_e32 v89, v89
	v_mul_f32_e32 v88, v101, v88
	v_mul_f32_e32 v103, v220, v103
	v_cvt_pk_bf16_f32 v88, v103, v88
	v_cndmask_b32_e64 v101, v89, v87, s[36:37]
	v_cndmask_b32_e64 v87, v87, v89, s[36:37]
	v_mul_f32_e32 v87, v98, v87
	ds_write_b16 v148, v88 offset:20400
	ds_write_b16_d16_hi v148, v88 offset:2992
	v_mul_f32_e32 v101, v218, v101
	v_cvt_pk_bf16_f32 v87, v101, v87
	ds_write_b16 v148, v87 offset:20672
	ds_write_b16_d16_hi v148, v87 offset:3264
	v_and_b32_e32 v89, 0xffff, v87
	v_max_f32_e32 v87, 0x5bf68a9, v86
	v_rcp_f32_e32 v87, v87
	s_nop 0
	v_cndmask_b32_e64 v98, v87, v86, s[36:37]
	v_cndmask_b32_e64 v86, v86, v87, s[36:37]
	v_max_f32_e32 v87, 0x5bf68a9, v85
	v_rcp_f32_e32 v87, v87
	v_mul_f32_e32 v86, v96, v86
	v_mul_f32_e32 v98, v130, v98
	v_cvt_pk_bf16_f32 v86, v98, v86
	v_cndmask_b32_e64 v96, v87, v85, s[36:37]
	v_cndmask_b32_e64 v85, v85, v87, s[36:37]
	v_mul_f32_e32 v85, v94, v85
	ds_write_b16 v148, v86 offset:20944
	ds_write_b16_d16_hi v148, v86 offset:3536
	v_mul_f32_e32 v96, v127, v96
	v_cvt_pk_bf16_f32 v85, v96, v85
	ds_write_b16 v148, v85 offset:21216
	ds_write_b16_d16_hi v148, v85 offset:3808
	v_and_b32_e32 v87, 0xffff, v85
	v_cndmask_b32_e64 v85, v84, v66, s[36:37]
	v_cndmask_b32_e64 v66, v66, v84, s[36:37]
	v_mul_f32_e32 v66, v92, v66
	v_mul_f32_e32 v85, v123, v85
	v_cvt_pk_bf16_f32 v84, v85, v66
	v_lshl_or_b32 v66, v122, 16, v67
	v_lshl_or_b32 v67, v100, 16, v126
	ds_write_b16 v148, v84 offset:21488
	ds_write_b16_d16_hi v148, v84 offset:4080
	ds_write2_b64 v74, v[66:67], v[70:71] offset1:2
	v_lshl_or_b32 v66, v90, 16, v95
	v_lshl_or_b32 v67, v88, 16, v91
	v_lshl_or_b32 v70, v86, 16, v89
	v_lshl_or_b32 v71, v84, 16, v87
	ds_write2_b64 v75, v[68:69], v[72:73] offset1:2
	v_lshl_or_b32 v68, v77, 16, v76
	v_lshl_or_b32 v69, v79, 16, v78
	v_lshl_or_b32 v72, v81, 16, v80
	v_lshl_or_b32 v73, v83, 16, v82
	ds_write2_b64 v74, v[66:67], v[70:71] offset0:4 offset1:6
	ds_write2_b64 v75, v[68:69], v[72:73] offset0:4 offset1:6
	s_waitcnt lgkmcnt(0)
	s_waitcnt lgkmcnt(0)
	s_barrier
	s_and_saveexec_b64 s[56:57], s[54:55]
	s_cbranch_execz .LBB0_651
	s_waitcnt vmcnt(3)
	v_max3_f32 v66, v162, v163, v164
	v_sub_f32_e32 v67, v162, v66
	v_sub_f32_e32 v68, v163, v66
	v_mul_f32_e32 v67, 0x3fb8aa3b, v67
	v_mul_f32_e32 v68, 0x3fb8aa3b, v68
	v_sub_f32_e32 v66, v164, v66
	v_exp_f32_e32 v67, v67
	v_exp_f32_e32 v69, v68
	v_mul_f32_e32 v66, 0x3fb8aa3b, v66
	v_exp_f32_e32 v66, v66
	s_waitcnt vmcnt(1)
	v_and_b32_e32 v72, 0xffff0000, v8
	v_add_f32_e32 v68, v67, v69
	v_lshlrev_b32_e32 v73, 16, v9
	v_add_f32_e32 v68, v66, v68
	v_rcp_f32_e32 v68, v68
	v_and_b32_e32 v75, 0xffff0000, v9
	v_lshlrev_b32_e32 v76, 16, v10
	v_and_b32_e32 v77, 0xffff0000, v10
	v_mul_f32_e32 v74, v69, v68
	v_lshlrev_b32_e32 v69, 16, v8
	v_pk_mul_f32 v[70:71], v[66:67], v[68:69] op_sel_hi:[1,0]
	v_lshlrev_b32_e32 v67, 16, v4
	s_waitcnt vmcnt(0)
	v_lshlrev_b32_e32 v66, 16, v12
	v_pk_mul_f32 v[66:67], v[70:71], v[66:67]
	v_lshlrev_b32_e32 v78, 16, v11
	v_fma_f32 v67, v74, v69, v67
	v_add_f32_e32 v68, v66, v67
	v_and_b32_e32 v67, 0xffff0000, v4
	v_and_b32_e32 v66, 0xffff0000, v12
	v_pk_mul_f32 v[66:67], v[70:71], v[66:67]
	v_lshlrev_b32_e32 v69, 16, v5
	v_fma_f32 v67, v74, v72, v67
	v_add_f32_e32 v66, v66, v67
	v_cvt_pk_bf16_f32 v66, v68, v66
	v_lshlrev_b32_e32 v68, 16, v13
	v_pk_mul_f32 v[68:69], v[70:71], v[68:69]
	v_lshlrev_b64 v[64:65], 12, v[64:65]
	v_fma_f32 v67, v74, v73, v69
	v_add_f32_e32 v67, v68, v67
	v_and_b32_e32 v69, 0xffff0000, v5
	v_and_b32_e32 v68, 0xffff0000, v13
	v_pk_mul_f32 v[68:69], v[70:71], v[68:69]
	v_lshlrev_b32_e32 v73, 16, v7
	v_fma_f32 v69, v74, v75, v69
	v_add_f32_e32 v68, v68, v69
	v_cvt_pk_bf16_f32 v67, v67, v68
	v_lshlrev_b32_e32 v69, 16, v6
	v_lshlrev_b32_e32 v68, 16, v14
	v_pk_mul_f32 v[68:69], v[70:71], v[68:69]
	v_and_b32_e32 v75, 0xffff0000, v11
	v_fma_f32 v69, v74, v76, v69
	v_add_f32_e32 v72, v68, v69
	v_and_b32_e32 v69, 0xffff0000, v6
	v_and_b32_e32 v68, 0xffff0000, v14
	v_pk_mul_f32 v[68:69], v[70:71], v[68:69]
	v_lshl_add_u64 v[64:65], v[110:111], 0, v[64:65]
	v_fma_f32 v69, v74, v77, v69
	v_add_f32_e32 v68, v68, v69
	v_cvt_pk_bf16_f32 v68, v72, v68
	v_lshlrev_b32_e32 v72, 16, v15
	v_pk_mul_f32 v[72:73], v[70:71], v[72:73]
	s_nop 0
	v_fma_f32 v69, v74, v78, v73
	v_add_f32_e32 v69, v72, v69
	v_and_b32_e32 v73, 0xffff0000, v7
	v_and_b32_e32 v72, 0xffff0000, v15
	v_pk_mul_f32 v[70:71], v[70:71], v[72:73]
	s_nop 0
	v_fma_f32 v71, v74, v75, v71
	v_add_f32_e32 v70, v70, v71
	v_cvt_pk_bf16_f32 v69, v69, v70
	global_store_dwordx4 v[64:65], v[66:69], off

.LBB0_676:
	s_or_b64 exec, exec, s[56:57]
	ds_read_b128 v[100:103], v152 offset:34816
	ds_read_b128 v[218:221], v152 offset:34880
	s_waitcnt lgkmcnt(2)
	ds_read_b128 v[32:35], v153 offset:53248
	ds_read_b128 v[36:39], v153 offset:53312
	ds_read_b128 v[44:47], v153 offset:55616
	ds_read_b128 v[48:51], v153 offset:57920
	s_mov_b32 s4, 0xf800000
	s_waitcnt lgkmcnt(3)
	v_mfma_f32_16x16x32_bf16 v[32:35], v[100:103], v[32:35], v[60:63]
	s_waitcnt lgkmcnt(2)
	v_mfma_f32_16x16x32_bf16 v[32:35], v[218:221], v[36:39], v[32:35]
	ds_read_b128 v[36:39], v153 offset:55552
	ds_read_b128 v[60:63], v153 offset:60224
	s_waitcnt lgkmcnt(1)
	v_mfma_f32_16x16x32_bf16 v[36:39], v[100:103], v[36:39], v[68:71]
	s_nop 2
	ds_read_b128 v[68:71], v153 offset:64832
	v_mfma_f32_16x16x32_bf16 v[36:39], v[218:221], v[44:47], v[36:39]
	ds_read_b128 v[44:47], v153 offset:57856
	s_waitcnt lgkmcnt(0)
	v_mfma_f32_16x16x32_bf16 v[44:47], v[100:103], v[44:47], v[88:91]
	v_mfma_f32_16x16x32_bf16 v[44:47], v[218:221], v[48:51], v[44:47]
	ds_read_b128 v[48:51], v153 offset:60160
	s_waitcnt lgkmcnt(0)
	v_mfma_f32_16x16x32_bf16 v[48:51], v[100:103], v[48:51], v[84:87]
	v_mfma_f32_16x16x32_bf16 v[48:51], v[218:221], v[60:63], v[48:51]
	ds_read_b128 v[60:63], v153 offset:62464
	s_waitcnt lgkmcnt(0)
	v_mfma_f32_16x16x32_bf16 v[52:55], v[100:103], v[60:63], v[52:55]
	ds_read_b128 v[60:63], v153 offset:62528
	s_waitcnt lgkmcnt(0)
	v_mfma_f32_16x16x32_bf16 v[52:55], v[218:221], v[60:63], v[52:55]
	ds_read_b128 v[60:63], v153 offset:64768
	s_waitcnt lgkmcnt(0)
	v_mfma_f32_16x16x32_bf16 v[60:63], v[100:103], v[60:63], v[80:83]
	v_mfma_f32_16x16x32_bf16 v[68:71], v[218:221], v[68:71], v[60:63]
	s_nop 6
	ds_read_b128 v[60:63], v154 offset:62464
	s_waitcnt lgkmcnt(0)
	v_mfma_f32_16x16x32_bf16 v[60:63], v[100:103], v[60:63], v[72:75]
	s_nop 2
	ds_read_b128 v[72:75], v154 offset:62528
	s_waitcnt lgkmcnt(0)
	v_mfma_f32_16x16x32_bf16 v[72:75], v[218:221], v[72:75], v[60:63]
	s_nop 2
	ds_read_b128 v[60:63], v154 offset:64768
	s_waitcnt lgkmcnt(0)
	v_mfma_f32_16x16x32_bf16 v[60:63], v[100:103], v[60:63], v[76:79]
	s_nop 2
	ds_read_b128 v[76:79], v154 offset:64832
	s_waitcnt lgkmcnt(0)
	s_waitcnt lgkmcnt(0)
	v_mfma_f32_16x16x32_bf16 v[76:79], v[218:221], v[76:79], v[60:63]
	s_barrier
	s_nop 1
	ds_read2st64_b32 v[60:61], v145 offset1:1
	s_waitcnt lgkmcnt(0)
	v_add_f32_e32 v60, v60, v61
	v_fmamk_f32 v60, v60, 0x3c000000, v232
	v_cmp_gt_f32_e32 vcc, s4, v60
	v_mul_f32_e32 v61, 0x4f800000, v60
	s_nop 0
	v_cndmask_b32_e32 v60, v60, v61, vcc
	v_sqrt_f32_e32 v61, v60
	s_nop 0
	v_add_u32_e32 v62, -1, v61
	v_fma_f32 v63, -v62, v61, v60
	v_cmp_ge_f32_e64 s[56:57], 0, v63
	v_add_u32_e32 v63, 1, v61
	s_nop 0
	v_cndmask_b32_e64 v62, v61, v62, s[56:57]
	v_fma_f32 v61, -v63, v61, v60
	v_cmp_lt_f32_e64 s[56:57], 0, v61
	s_nop 1
	v_cndmask_b32_e64 v61, v62, v63, s[56:57]
	v_mul_f32_e32 v62, 0x37800000, v61
	v_cndmask_b32_e32 v61, v61, v62, vcc
	v_mov_b32_e32 v62, 0x260
	v_cmp_class_f32_e32 vcc, v60, v62
	s_nop 1
	v_cndmask_b32_e32 v60, v61, v60, vcc
	v_rcp_f32_e32 v61, v60
	s_nop 0
	s_waitcnt vmcnt(3)
	v_lshlrev_b32_e32 v62, 16, v130
	v_mul_f32_e32 v63, 0xbfb8aa3b, v62
	v_exp_f32_e32 v63, v63
	v_mov_b32_e32 v60, v61
	v_mul_f32_e32 v61, v96, v60
	v_mul_f32_e32 v61, v16, v61
	v_add_f32_e32 v63, 1.0, v63
	v_rcp_f32_e32 v80, v63
	v_mul_f32_e32 v56, v56, v60
	v_mul_f32_e32 v56, v24, v56
	v_mul_f32_e32 v57, v57, v60
	v_mul_f32_e32 v62, v62, v80
	v_and_b32_e32 v63, 0xffff0000, v130
	v_mul_f32_e32 v80, 0xbfb8aa3b, v63
	v_exp_f32_e32 v80, v80
	v_mul_f32_e32 v61, v62, v61
	v_mul_f32_e32 v62, v97, v60
	v_mul_f32_e32 v62, v17, v62
	v_add_f32_e32 v80, 1.0, v80
	v_rcp_f32_e32 v81, v80
	v_mul_f32_e32 v57, v25, v57
	v_mul_f32_e32 v40, v40, v60
	v_mul_f32_e32 v40, v28, v40
	v_mul_f32_e32 v63, v63, v81
	v_mul_f32_e32 v62, v63, v62
	v_lshlrev_b32_e32 v63, 16, v131
	v_mul_f32_e32 v80, 0xbfb8aa3b, v63
	v_exp_f32_e32 v80, v80
	v_cvt_pk_bf16_f32 v62, v61, v62
	v_mul_f32_e32 v61, v98, v60
	v_mul_f32_e32 v61, v18, v61
	v_add_f32_e32 v80, 1.0, v80
	v_rcp_f32_e32 v81, v80
	v_mul_f32_e32 v41, v41, v60
	v_mul_f32_e32 v41, v29, v41
	v_mul_f32_e32 v63, v63, v81
	v_and_b32_e32 v80, 0xffff0000, v131
	v_mul_f32_e32 v81, 0xbfb8aa3b, v80
	v_exp_f32_e32 v81, v81
	v_mul_f32_e32 v61, v63, v61
	v_mul_f32_e32 v63, v99, v60
	v_mul_f32_e32 v63, v19, v63
	v_add_f32_e32 v81, 1.0, v81
	v_rcp_f32_e32 v82, v81
	s_nop 0
	v_mul_f32_e32 v80, v80, v82
	v_mul_f32_e32 v63, v80, v63
	v_cvt_pk_bf16_f32 v63, v61, v63
	ds_write_b64 v155, v[62:63]
	s_waitcnt vmcnt(2)
	v_lshlrev_b32_e32 v62, 16, v128
	v_mul_f32_e32 v63, 0xbfb8aa3b, v62
	v_exp_f32_e32 v63, v63
	v_mul_f32_e32 v61, v92, v60
	v_mul_f32_e32 v61, v20, v61
	v_add_f32_e32 v63, 1.0, v63
	v_rcp_f32_e32 v80, v63
	s_nop 0
	v_mul_f32_e32 v62, v62, v80
	v_and_b32_e32 v63, 0xffff0000, v128
	v_mul_f32_e32 v80, 0xbfb8aa3b, v63
	v_exp_f32_e32 v80, v80
	v_mul_f32_e32 v61, v62, v61
	v_mul_f32_e32 v62, v93, v60
	v_mul_f32_e32 v62, v21, v62
	v_add_f32_e32 v80, 1.0, v80
	v_rcp_f32_e32 v81, v80
	s_nop 0
	v_mul_f32_e32 v63, v63, v81
	v_mul_f32_e32 v62, v63, v62
	v_lshlrev_b32_e32 v63, 16, v129
	v_mul_f32_e32 v80, 0xbfb8aa3b, v63
	v_exp_f32_e32 v80, v80
	v_cvt_pk_bf16_f32 v62, v61, v62
	v_mul_f32_e32 v61, v94, v60
	v_mul_f32_e32 v61, v22, v61
	v_add_f32_e32 v80, 1.0, v80
	v_rcp_f32_e32 v81, v80
	s_nop 0
	v_mul_f32_e32 v63, v63, v81
	v_and_b32_e32 v80, 0xffff0000, v129
	v_mul_f32_e32 v81, 0xbfb8aa3b, v80
	v_exp_f32_e32 v81, v81
	v_mul_f32_e32 v61, v63, v61
	v_mul_f32_e32 v63, v95, v60
	v_mul_f32_e32 v63, v23, v63
	v_add_f32_e32 v81, 1.0, v81
	v_rcp_f32_e32 v82, v81
	s_nop 0
	v_mul_f32_e32 v80, v80, v82
	v_mul_f32_e32 v63, v80, v63
	v_cvt_pk_bf16_f32 v63, v61, v63
	s_waitcnt vmcnt(1)
	v_lshlrev_b32_e32 v61, 16, v126
	ds_write_b64 v156, v[62:63]
	v_mul_f32_e32 v62, 0xbfb8aa3b, v61
	v_exp_f32_e32 v62, v62
	s_nop 0
	v_add_f32_e32 v62, 1.0, v62
	v_rcp_f32_e32 v63, v62
	s_nop 0
	v_mul_f32_e32 v61, v61, v63
	v_mul_f32_e32 v56, v61, v56
	v_and_b32_e32 v61, 0xffff0000, v126
	v_mul_f32_e32 v62, 0xbfb8aa3b, v61
	v_exp_f32_e32 v62, v62
	s_nop 0
	v_add_f32_e32 v62, 1.0, v62
	v_rcp_f32_e32 v63, v62
	s_nop 0
	v_mul_f32_e32 v61, v61, v63
	v_mul_f32_e32 v57, v61, v57
	v_cvt_pk_bf16_f32 v56, v56, v57
	v_mul_f32_e32 v57, v58, v60
	v_lshlrev_b32_e32 v58, 16, v127
	v_mul_f32_e32 v61, 0xbfb8aa3b, v58
	v_exp_f32_e32 v61, v61
	v_mul_f32_e32 v57, v26, v57
	v_add_f32_e32 v61, 1.0, v61
	v_rcp_f32_e32 v62, v61
	s_nop 0
	v_mul_f32_e32 v58, v58, v62
	v_mul_f32_e32 v57, v58, v57
	v_mul_f32_e32 v58, v59, v60
	v_and_b32_e32 v59, 0xffff0000, v127
	v_mul_f32_e32 v61, 0xbfb8aa3b, v59
	v_exp_f32_e32 v61, v61
	v_mul_f32_e32 v58, v27, v58
	v_add_f32_e32 v61, 1.0, v61
	v_rcp_f32_e32 v62, v61
	s_nop 0
	v_mul_f32_e32 v59, v59, v62
	v_mul_f32_e32 v58, v59, v58
	v_cvt_pk_bf16_f32 v57, v57, v58
	ds_write_b64 v157, v[56:57]
	s_waitcnt vmcnt(0)
	v_lshlrev_b32_e32 v56, 16, v124
	v_mul_f32_e32 v57, 0xbfb8aa3b, v56
	v_exp_f32_e32 v57, v57
	s_nop 0
	v_add_f32_e32 v57, 1.0, v57
	v_rcp_f32_e32 v58, v57
	s_nop 0
	v_mul_f32_e32 v56, v56, v58
	v_mul_f32_e32 v40, v56, v40
	v_and_b32_e32 v56, 0xffff0000, v124
	v_mul_f32_e32 v57, 0xbfb8aa3b, v56
	v_exp_f32_e32 v57, v57
	s_nop 0
	v_add_f32_e32 v57, 1.0, v57
	v_rcp_f32_e32 v58, v57
	s_nop 0
	v_mul_f32_e32 v56, v56, v58
	v_mul_f32_e32 v41, v56, v41
	v_cvt_pk_bf16_f32 v40, v40, v41
	v_mul_f32_e32 v41, v42, v60
	v_lshlrev_b32_e32 v42, 16, v125
	v_mul_f32_e32 v56, 0xbfb8aa3b, v42
	v_exp_f32_e32 v56, v56
	v_mul_f32_e32 v41, v30, v41
	v_add_f32_e32 v56, 1.0, v56
	v_rcp_f32_e32 v57, v56
	s_nop 0
	v_mul_f32_e32 v42, v42, v57
	v_mul_f32_e32 v41, v42, v41
	v_mul_f32_e32 v42, v43, v60
	v_and_b32_e32 v43, 0xffff0000, v125
	v_mul_f32_e32 v56, 0xbfb8aa3b, v43
	v_exp_f32_e32 v56, v56
	v_mul_f32_e32 v42, v31, v42
	v_add_f32_e32 v56, 1.0, v56
	v_rcp_f32_e32 v57, v56
	s_nop 0
	v_mul_f32_e32 v43, v43, v57
	v_mul_f32_e32 v42, v43, v42
	v_cvt_pk_bf16_f32 v41, v41, v42
	ds_write_b64 v158, v[40:41]
	s_waitcnt lgkmcnt(0)
	ds_read_b128 v[40:43], v159
	ds_read_b128 v[56:59], v159 offset:1024
	v_add_u32_e32 v60, s91, v166
	v_ashrrev_i32_e32 v61, 31, v60
	s_waitcnt lgkmcnt(0)
	v_lshlrev_b64 v[60:61], 12, v[60:61]
	v_lshl_add_u64 v[60:61], v[120:121], 0, v[60:61]
	s_waitcnt lgkmcnt(1)
	global_store_dwordx4 v[60:61], v[40:43], off offset:2048
	s_nop 1
	v_add_co_u32_e32 v40, vcc, 0x8000, v60
	s_nop 1
	v_addc_co_u32_e32 v41, vcc, 0, v61, vcc
	s_waitcnt lgkmcnt(0)
	global_store_dwordx4 v[40:41], v[56:59], off offset:2048
	s_and_saveexec_b64 s[56:57], s[54:55]
	s_cbranch_execz .LBB0_678
	v_max3_f32 v40, v162, v163, v164
	v_sub_f32_e32 v41, v162, v40
	v_sub_f32_e32 v42, v163, v40
	v_mul_f32_e32 v41, 0x3fb8aa3b, v41
	v_mul_f32_e32 v42, 0x3fb8aa3b, v42
	v_sub_f32_e32 v40, v164, v40
	v_exp_f32_e32 v41, v41
	v_exp_f32_e32 v43, v42
	v_mul_f32_e32 v40, 0x3fb8aa3b, v40
	v_exp_f32_e32 v40, v40
	v_and_b32_e32 v58, 0xffff0000, v8
	v_add_f32_e32 v42, v41, v43
	v_lshlrev_b32_e32 v59, 16, v9
	v_add_f32_e32 v42, v40, v42
	v_rcp_f32_e32 v42, v42
	v_and_b32_e32 v61, 0xffff0000, v9
	v_lshlrev_b32_e32 v62, 16, v10
	v_and_b32_e32 v63, 0xffff0000, v10
	v_mul_f32_e32 v60, v43, v42
	v_lshlrev_b32_e32 v43, 16, v8
	v_pk_mul_f32 v[56:57], v[40:41], v[42:43] op_sel_hi:[1,0]
	v_lshlrev_b32_e32 v41, 16, v4
	v_lshlrev_b32_e32 v40, 16, v12
	v_pk_mul_f32 v[40:41], v[56:57], v[40:41]
	v_lshlrev_b32_e32 v80, 16, v11
	v_fma_f32 v41, v60, v43, v41
	v_add_f32_e32 v42, v40, v41
	v_and_b32_e32 v41, 0xffff0000, v4
	v_and_b32_e32 v40, 0xffff0000, v12
	v_pk_mul_f32 v[40:41], v[56:57], v[40:41]
	v_lshlrev_b32_e32 v43, 16, v5
	v_fma_f32 v41, v60, v58, v41
	v_add_f32_e32 v40, v40, v41
	v_cvt_pk_bf16_f32 v40, v42, v40
	v_lshlrev_b32_e32 v42, 16, v13
	v_pk_mul_f32 v[42:43], v[56:57], v[42:43]
	s_nop 0
	v_fma_f32 v41, v60, v59, v43
	v_add_f32_e32 v41, v42, v41
	v_and_b32_e32 v43, 0xffff0000, v5
	v_and_b32_e32 v42, 0xffff0000, v13
	v_pk_mul_f32 v[42:43], v[56:57], v[42:43]
	v_lshlrev_b32_e32 v59, 16, v7
	v_fma_f32 v43, v60, v61, v43
	v_add_f32_e32 v42, v42, v43
	v_cvt_pk_bf16_f32 v41, v41, v42
	v_lshlrev_b32_e32 v43, 16, v6
	v_lshlrev_b32_e32 v42, 16, v14
	v_pk_mul_f32 v[42:43], v[56:57], v[42:43]
	v_and_b32_e32 v61, 0xffff0000, v11
	v_fma_f32 v43, v60, v62, v43
	v_add_f32_e32 v58, v42, v43
	v_and_b32_e32 v43, 0xffff0000, v6
	v_and_b32_e32 v42, 0xffff0000, v14
	v_pk_mul_f32 v[42:43], v[56:57], v[42:43]
	s_nop 0
	v_fma_f32 v43, v60, v63, v43
	v_add_f32_e32 v42, v42, v43
	v_cvt_pk_bf16_f32 v42, v58, v42
	v_lshlrev_b32_e32 v58, 16, v15
	v_pk_mul_f32 v[58:59], v[56:57], v[58:59]
	s_nop 0
	v_fma_f32 v43, v60, v80, v59
	v_add_f32_e32 v43, v58, v43
	v_and_b32_e32 v59, 0xffff0000, v7
	v_and_b32_e32 v58, 0xffff0000, v15
	v_pk_mul_f32 v[56:57], v[56:57], v[58:59]
	s_nop 0
	v_fma_f32 v57, v60, v61, v57
	v_add_f32_e32 v56, v56, v57
	v_cvt_pk_bf16_f32 v43, v43, v56
	v_lshlrev_b64 v[56:57], 12, v[122:123]
	v_lshl_add_u64 v[56:57], v[110:111], 0, v[56:57]
	global_store_dwordx4 v[56:57], v[40:43], off
